# 4 of the 11 grid barriers (P3-P4, P4-P5, P8-P9, P9-P10: producer and consumer tiles share row panels within the 32 workgroups of equal blockIdx&7) replaced by a 32-workgroup barrier with the same rele
# baseline (speedup 1.0000x reference)
; __device__ __forceinline__ unsigned xb_ld(unsigned* p)              { return __hip_atomic_load(p, __ATOMIC_RELAXED, __HIP_MEMORY_SCOPE_AGENT); }
; __device__ __forceinline__ unsigned xb_add(unsigned* p, unsigned v) { return __hip_atomic_fetch_add(p, v, __ATOMIC_RELAXED, __HIP_MEMORY_SCOPE_AGENT); }
; #define XB_SPIN(cond, bar) do { unsigned _sp = 0; while (cond) { __builtin_amdgcn_s_sleep(1); \
;     if ((++_sp & 255u) == 0u) { if (xb_ld(&(bar)[XB_TMO])) break; if (_sp > XB_SPIN_CAP) { atomicAdd(&(bar)[XB_TMO], 1u); break; } } } } while (0)
; __device__ __forceinline__ void xcd_barrier(const XcdBarrier& b) {
;     asm volatile("s_waitcnt vmcnt(0)" ::: "memory");
;     __syncthreads();
;     if (threadIdx.x == 0) {
;         unsigned* bar = b.bar;
;         __builtin_amdgcn_s_waitcnt(0);
;         unsigned nloc = b.st[0], nx = b.st[1];
;         if (nloc == 0u) { xcd_barrier_complete(bar, b.x, nloc, nx); b.st[0] = nloc; b.st[1] = nx; }
;         const unsigned old = xb_add(&bar[XB_XSUB(b.x)], 1u);
;         const unsigned gen = old / nloc;
;         if (old + 1u == (gen + 1u) * nloc) {
;             __builtin_amdgcn_fence(__ATOMIC_RELEASE, "agent");
;             asm volatile("s_waitcnt vmcnt(0)" ::: "memory");
;             const unsigned og = xb_add(&bar[XB_TOP], 1u);
;             const unsigned tg = og / nx;
;             if (og + 1u == (tg + 1u) * nx) xb_add(&bar[XB_TOPGEN], 1u);
;             else XB_SPIN(xb_ld(&bar[XB_TOPGEN]) == tg, bar);
;             __builtin_amdgcn_fence(__ATOMIC_ACQUIRE, "agent");
;             xb_add(&bar[XB_XGEN(b.x)], 1u);
;             asm volatile("s_waitcnt vmcnt(0)" ::: "memory");
;         } else {
;             XB_SPIN(xb_ld(&bar[XB_XGEN(b.x)]) == gen, bar);
;             __builtin_amdgcn_fence(__ATOMIC_ACQUIRE, "agent");
;             asm volatile("s_waitcnt vmcnt(0)" ::: "memory");
;         }
.LBB0_315:
	s_waitcnt vmcnt(0)
	s_waitcnt lgkmcnt(0)
	s_barrier
	s_and_saveexec_b64 s[8:9], s[4:5]
	s_cbranch_execz .LBB0_367
	buffer_wbl2 sc1
	s_waitcnt vmcnt(0) lgkmcnt(0)
	s_and_b32 s10, s2, 7
	s_lshl_b32 s10, s10, 8
	s_add_i32 s10, s10, 0x180480
	v_mov_b32_e32 v0, s10
	v_mov_b32_e32 v1, 1
	global_atomic_add v2, v0, v1, s[18:19] sc0
	s_waitcnt vmcnt(0)
	v_lshrrev_b32_e32 v2, 5, v2
	v_add_u32_e32 v2, 1, v2
	v_lshlrev_b32_e32 v2, 5, v2
	s_nop 0
	v_readfirstlane_b32 s11, v2
	s_mov_b32 s26, 0
.Lgb_spin_0:
	global_load_dword v3, v0, s[18:19] sc1
	s_waitcnt vmcnt(0)
	s_nop 0
	v_readfirstlane_b32 s27, v3
	s_cmp_ge_u32 s27, s11
	s_cbranch_scc1 .Lgb_done_0
	s_sleep 1
	s_add_i32 s26, s26, 1
	s_cmp_lt_u32 s26, 0x4000
	s_cbranch_scc1 .Lgb_spin_0
.Lgb_done_0:
	buffer_inv sc1
	s_waitcnt vmcnt(0)

; __device__ __forceinline__ unsigned xb_ld(unsigned* p)              { return __hip_atomic_load(p, __ATOMIC_RELAXED, __HIP_MEMORY_SCOPE_AGENT); }
; __device__ __forceinline__ unsigned xb_add(unsigned* p, unsigned v) { return __hip_atomic_fetch_add(p, v, __ATOMIC_RELAXED, __HIP_MEMORY_SCOPE_AGENT); }
; #define XB_SPIN(cond, bar) do { unsigned _sp = 0; while (cond) { __builtin_amdgcn_s_sleep(1); \
;     if ((++_sp & 255u) == 0u) { if (xb_ld(&(bar)[XB_TMO])) break; if (_sp > XB_SPIN_CAP) { atomicAdd(&(bar)[XB_TMO], 1u); break; } } } } while (0)
; __device__ __forceinline__ void xcd_barrier(const XcdBarrier& b) {
;     asm volatile("s_waitcnt vmcnt(0)" ::: "memory");
;     __syncthreads();
;     if (threadIdx.x == 0) {
;         unsigned* bar = b.bar;
;         __builtin_amdgcn_s_waitcnt(0);
;         unsigned nloc = b.st[0], nx = b.st[1];
;         if (nloc == 0u) { xcd_barrier_complete(bar, b.x, nloc, nx); b.st[0] = nloc; b.st[1] = nx; }
;         const unsigned old = xb_add(&bar[XB_XSUB(b.x)], 1u);
;         const unsigned gen = old / nloc;
;         if (old + 1u == (gen + 1u) * nloc) {
;             __builtin_amdgcn_fence(__ATOMIC_RELEASE, "agent");
;             asm volatile("s_waitcnt vmcnt(0)" ::: "memory");
;             const unsigned og = xb_add(&bar[XB_TOP], 1u);
;             const unsigned tg = og / nx;
;             if (og + 1u == (tg + 1u) * nx) xb_add(&bar[XB_TOPGEN], 1u);
;             else XB_SPIN(xb_ld(&bar[XB_TOPGEN]) == tg, bar);
;             __builtin_amdgcn_fence(__ATOMIC_ACQUIRE, "agent");
;             xb_add(&bar[XB_XGEN(b.x)], 1u);
;             asm volatile("s_waitcnt vmcnt(0)" ::: "memory");
;         } else {
;             XB_SPIN(xb_ld(&bar[XB_XGEN(b.x)]) == gen, bar);
;             __builtin_amdgcn_fence(__ATOMIC_ACQUIRE, "agent");
;             asm volatile("s_waitcnt vmcnt(0)" ::: "memory");
;         }
.LBB0_401:
	s_waitcnt vmcnt(0)
	s_waitcnt vmcnt(0)
	s_barrier
	s_and_saveexec_b64 s[8:9], s[4:5]
	s_cbranch_execz .LBB0_453
	buffer_wbl2 sc1
	s_waitcnt vmcnt(0) lgkmcnt(0)
	s_and_b32 s10, s2, 7
	s_lshl_b32 s10, s10, 8
	s_add_i32 s10, s10, 0x180480
	v_mov_b32_e32 v0, s10
	v_mov_b32_e32 v1, 1
	global_atomic_add v2, v0, v1, s[18:19] sc0
	s_waitcnt vmcnt(0)
	v_lshrrev_b32_e32 v2, 5, v2
	v_add_u32_e32 v2, 1, v2
	v_lshlrev_b32_e32 v2, 5, v2
	s_nop 0
	v_readfirstlane_b32 s11, v2
	s_mov_b32 s26, 0
